# up epilogue H stores with cache policy 'sc1 nt' (policy sweep), on top of v59
# speedup vs baseline: 1.0081x; 1.0081x over previous
; __device__ __forceinline__ unsigned cvt_pk_bf16(float lo, float hi) { unsigned r; asm volatile("v_cvt_pk_bf16_f32 %0, %1, %2" : "=v"(r) : "v"(lo), "v"(hi)); return r; }
;     __device__ __forceinline__ void operator()(const f32x4 (&acc)[2][2][4][2], const Unit& u, int ui, int wr, int wc, int fr, int fq) const {
;     ...
;             for (int m = 0; m < 4; ++m) rs[ai][m] = row_rstd(lds, ui, ai * HALF + wr * 64 + m * 16 + fr);
; #pragma unroll
;         for (int ai = 0; ai < 2; ++ai)
; #pragma unroll
;             for (int m = 0; m < 4; ++m) { const float r = rs[ai][m]; const int row = row0 + ai * HALF + m * 16;
;                 const float c1 = r * -1.44269504089f, r2 = r * r; u32x4 w;
; #pragma unroll
;                 for (int n = 0; n < 2; ++n)
; #pragma unroll
;                     for (int p = 0; p < 2; ++p) { const f32x2 g = (f32x2){acc[ai][0][m][n][2 * p], acc[ai][0][m][n][2 * p + 1]}, uu = (f32x2){acc[ai][1][m][n][2 * p], acc[ai][1][m][n][2 * p + 1]};
;                         const f32x2 t = g * c1; f32x2 d; d.x = __builtin_amdgcn_exp2f(t.x); d.y = __builtin_amdgcn_exp2f(t.y); d = d + 1.0f;
;                         f32x2 q; q.x = __builtin_amdgcn_rcpf(d.x); q.y = __builtin_amdgcn_rcpf(d.y);
;                         const f32x2 hh = (g * uu) * (q * r2); w[2 * n + p] = cvt_pk_bf16(hh.x, hh.y); }
;                 __builtin_nontemporal_store(w, (u32x4*)(H + (size_t)row * ldh + col0)); }
.LBB0_449:
	v_mov_b32_e32 v140, v147
	v_mov_b32_e32 v167, v164
	v_pk_mul_f32 v[120:121], v[124:125], v[120:121]
	v_add_u32_e32 v171, s35, v140
	v_lshlrev_b32_e32 v140, 2, v171
	v_lshl_add_u32 v140, s48, 10, v140
	v_add_u32_e32 v140, 0x20400, v140
	ds_read2_b32 v[168:169], v140 offset1:16
	ds_read2_b32 v[162:163], v140 offset0:32 offset1:48
	ds_read2_b32 v[142:143], v140 offset0:128 offset1:144
	ds_read2_b32 v[140:141], v140 offset0:160 offset1:176
	v_pk_mul_f32 v[122:123], v[126:127], v[122:123]
	s_waitcnt lgkmcnt(0)
	v_mul_f32_e32 v172, 0xbfb8aa3b, v168
	v_pk_mul_f32 v[174:175], v[124:125], v[172:173] op_sel_hi:[1,0]
	v_pk_mul_f32 v[124:125], v[126:127], v[172:173] op_sel_hi:[1,0]
	v_exp_f32_e32 v174, v174
	v_exp_f32_e32 v175, v175
	v_exp_f32_e32 v124, v124
	v_exp_f32_e32 v125, v125
	v_mul_f32_e32 v168, v168, v168
	v_pk_add_f32 v[174:175], v[174:175], 1.0 op_sel_hi:[1,0]
	v_pk_mul_f32 v[112:113], v[116:117], v[112:113]
	v_rcp_f32_e32 v174, v174
	v_rcp_f32_e32 v175, v175
	v_pk_add_f32 v[124:125], v[124:125], 1.0 op_sel_hi:[1,0]
	v_pk_mul_f32 v[114:115], v[118:119], v[114:115]
	v_rcp_f32_e32 v124, v124
	v_rcp_f32_e32 v125, v125
	v_pk_mul_f32 v[126:127], v[168:169], v[174:175] op_sel_hi:[0,1]
	v_pk_mul_f32 v[120:121], v[120:121], v[126:127]
	v_pk_mul_f32 v[126:127], v[116:117], v[172:173] op_sel_hi:[1,0]
	v_pk_mul_f32 v[124:125], v[168:169], v[124:125] op_sel_hi:[0,1]
	v_exp_f32_e32 v126, v126
	v_exp_f32_e32 v127, v127
	v_pk_mul_f32 v[122:123], v[122:123], v[124:125]
	v_pk_mul_f32 v[124:125], v[118:119], v[172:173] op_sel_hi:[1,0]
	v_cvt_pk_bf16_f32 v120, v120, v121
	v_cvt_pk_bf16_f32 v121, v122, v123
	v_pk_add_f32 v[122:123], v[126:127], 1.0 op_sel_hi:[1,0]
	v_exp_f32_e32 v124, v124
	v_exp_f32_e32 v125, v125
	v_rcp_f32_e32 v122, v122
	v_rcp_f32_e32 v123, v123
	s_lshl_b32 s5, s47, 7
	v_pk_add_f32 v[116:117], v[124:125], 1.0 op_sel_hi:[1,0]
	s_or_b32 s5, s5, s36
	v_rcp_f32_e32 v116, v116
	v_rcp_f32_e32 v117, v117
	v_pk_mul_f32 v[118:119], v[168:169], v[122:123] op_sel_hi:[0,1]
	v_pk_mul_f32 v[112:113], v[112:113], v[118:119]
	v_mul_f32_e32 v118, 0xbfb8aa3b, v169
	v_cvt_pk_bf16_f32 v122, v112, v113
	v_pk_mul_f32 v[112:113], v[168:169], v[116:117] op_sel_hi:[0,1]
	v_pk_mul_f32 v[124:125], v[108:109], v[118:119] op_sel_hi:[1,0]
	v_lshl_add_u32 v170, v167, 3, s5
	v_pk_mul_f32 v[112:113], v[114:115], v[112:113]
	v_exp_f32_e32 v124, v124
	v_exp_f32_e32 v125, v125
	v_lshl_add_u32 v167, s46, 8, v171
	v_ashrrev_i32_e32 v171, 31, v170
	v_cvt_pk_bf16_f32 v123, v112, v113
	v_mov_b64_e32 v[112:113], s[20:21]
	v_pk_mul_f32 v[104:105], v[108:109], v[104:105]
	v_pk_mul_f32 v[108:109], v[110:111], v[118:119] op_sel_hi:[1,0]
	v_mad_i64_i32 v[116:117], s[14:15], v167, s59, v[112:113]
	v_lshlrev_b64 v[114:115], 1, v[170:171]
	v_exp_f32_e32 v108, v108
	v_exp_f32_e32 v109, v109
	v_lshl_add_u64 v[116:117], v[116:117], 0, v[114:115]
	global_store_dwordx4 v[116:117], v[120:123], off sc1 nt
	v_mul_f32_e32 v116, v169, v169
	v_pk_add_f32 v[108:109], v[108:109], 1.0 op_sel_hi:[1,0]
	v_pk_add_f32 v[120:121], v[124:125], 1.0 op_sel_hi:[1,0]
	v_rcp_f32_e32 v108, v108
	v_rcp_f32_e32 v120, v120
	v_rcp_f32_e32 v121, v121
	v_rcp_f32_e32 v109, v109
	v_pk_mul_f32 v[106:107], v[110:111], v[106:107]
	v_pk_mul_f32 v[96:97], v[100:101], v[96:97]
	v_pk_mul_f32 v[110:111], v[116:117], v[120:121] op_sel_hi:[0,1]
	v_pk_mul_f32 v[104:105], v[104:105], v[110:111]
	v_pk_mul_f32 v[110:111], v[100:101], v[118:119] op_sel_hi:[1,0]
	v_pk_mul_f32 v[108:109], v[116:117], v[108:109] op_sel_hi:[0,1]
	v_exp_f32_e32 v110, v110
	v_exp_f32_e32 v111, v111
	v_pk_mul_f32 v[106:107], v[106:107], v[108:109]
	v_pk_mul_f32 v[108:109], v[102:103], v[118:119] op_sel_hi:[1,0]
	v_cvt_pk_bf16_f32 v104, v104, v105
	v_cvt_pk_bf16_f32 v105, v106, v107
	v_pk_add_f32 v[106:107], v[110:111], 1.0 op_sel_hi:[1,0]
	v_exp_f32_e32 v108, v108
	v_exp_f32_e32 v109, v109
	v_rcp_f32_e32 v106, v106
	v_rcp_f32_e32 v107, v107
	v_pk_mul_f32 v[98:99], v[102:103], v[98:99]
	v_pk_add_f32 v[100:101], v[108:109], 1.0 op_sel_hi:[1,0]
	v_pk_mul_f32 v[88:89], v[92:93], v[88:89]
	v_rcp_f32_e32 v100, v100
	v_rcp_f32_e32 v101, v101
	v_pk_mul_f32 v[102:103], v[116:117], v[106:107] op_sel_hi:[0,1]
	v_pk_mul_f32 v[96:97], v[96:97], v[102:103]
	v_pk_mul_f32 v[90:91], v[94:95], v[90:91]
	v_cvt_pk_bf16_f32 v106, v96, v97
	v_pk_mul_f32 v[96:97], v[116:117], v[100:101] op_sel_hi:[0,1]
	v_pk_mul_f32 v[96:97], v[98:99], v[96:97]
	v_mul_f32_e32 v98, 0xbfb8aa3b, v162
	v_pk_mul_f32 v[100:101], v[92:93], v[98:99] op_sel_hi:[1,0]
	v_pk_mul_f32 v[92:93], v[94:95], v[98:99] op_sel_hi:[1,0]
	v_exp_f32_e32 v100, v100
	v_exp_f32_e32 v101, v101
	v_exp_f32_e32 v92, v92
	v_exp_f32_e32 v93, v93
	v_cvt_pk_bf16_f32 v107, v96, v97
	v_pk_add_f32 v[100:101], v[100:101], 1.0 op_sel_hi:[1,0]
	v_add_u32_e32 v96, 16, v167
	v_rcp_f32_e32 v100, v100
	v_rcp_f32_e32 v101, v101
	v_mad_i64_i32 v[96:97], s[14:15], v96, s59, v[112:113]
	v_pk_add_f32 v[92:93], v[92:93], 1.0 op_sel_hi:[1,0]
	v_lshl_add_u64 v[96:97], v[96:97], 0, v[114:115]
	v_rcp_f32_e32 v92, v92
	v_rcp_f32_e32 v93, v93
	global_store_dwordx4 v[96:97], v[104:107], off sc1 nt
	v_mul_f32_e32 v96, v162, v162
	v_pk_mul_f32 v[94:95], v[96:97], v[100:101] op_sel_hi:[0,1]
	v_pk_mul_f32 v[88:89], v[88:89], v[94:95]
	v_pk_mul_f32 v[94:95], v[84:85], v[98:99] op_sel_hi:[1,0]
	v_pk_mul_f32 v[92:93], v[96:97], v[92:93] op_sel_hi:[0,1]
	v_exp_f32_e32 v94, v94
	v_exp_f32_e32 v95, v95
	v_pk_mul_f32 v[90:91], v[90:91], v[92:93]
	v_pk_mul_f32 v[92:93], v[86:87], v[98:99] op_sel_hi:[1,0]
	v_cvt_pk_bf16_f32 v88, v88, v89
	v_cvt_pk_bf16_f32 v89, v90, v91
	v_pk_add_f32 v[90:91], v[94:95], 1.0 op_sel_hi:[1,0]
	v_exp_f32_e32 v92, v92
; __device__ __forceinline__ unsigned cvt_pk_bf16(float lo, float hi) { unsigned r; asm volatile("v_cvt_pk_bf16_f32 %0, %1, %2" : "=v"(r) : "v"(lo), "v"(hi)); return r; }
;     __device__ __forceinline__ void operator()(const f32x4 (&acc)[2][2][4][2], const Unit& u, int ui, int wr, int wc, int fr, int fq) const {
;     ...
;             for (int m = 0; m < 4; ++m) { const float r = rs[ai][m]; const int row = row0 + ai * HALF + m * 16;
;                 const float c1 = r * -1.44269504089f, r2 = r * r; u32x4 w;
; #pragma unroll
;                 for (int n = 0; n < 2; ++n)
; #pragma unroll
;                     for (int p = 0; p < 2; ++p) { const f32x2 g = (f32x2){acc[ai][0][m][n][2 * p], acc[ai][0][m][n][2 * p + 1]}, uu = (f32x2){acc[ai][1][m][n][2 * p], acc[ai][1][m][n][2 * p + 1]};
;                         const f32x2 t = g * c1; f32x2 d; d.x = __builtin_amdgcn_exp2f(t.x); d.y = __builtin_amdgcn_exp2f(t.y); d = d + 1.0f;
;                         f32x2 q; q.x = __builtin_amdgcn_rcpf(d.x); q.y = __builtin_amdgcn_rcpf(d.y);
;                         const f32x2 hh = (g * uu) * (q * r2); w[2 * n + p] = cvt_pk_bf16(hh.x, hh.y); }
;                 __builtin_nontemporal_store(w, (u32x4*)(H + (size_t)row * ldh + col0)); }
	v_exp_f32_e32 v93, v93
	v_rcp_f32_e32 v90, v90
	v_rcp_f32_e32 v91, v91
	v_pk_mul_f32 v[80:81], v[84:85], v[80:81]
	v_pk_add_f32 v[84:85], v[92:93], 1.0 op_sel_hi:[1,0]
	v_pk_mul_f32 v[82:83], v[86:87], v[82:83]
	v_rcp_f32_e32 v84, v84
	v_rcp_f32_e32 v85, v85
	v_pk_mul_f32 v[86:87], v[96:97], v[90:91] op_sel_hi:[0,1]
	v_pk_mul_f32 v[80:81], v[80:81], v[86:87]
	v_pk_mul_f32 v[72:73], v[76:77], v[72:73]
	v_cvt_pk_bf16_f32 v90, v80, v81
	v_pk_mul_f32 v[80:81], v[96:97], v[84:85] op_sel_hi:[0,1]
	v_pk_mul_f32 v[80:81], v[82:83], v[80:81]
	v_mul_f32_e32 v82, 0xbfb8aa3b, v163
	v_pk_mul_f32 v[84:85], v[76:77], v[82:83] op_sel_hi:[1,0]
	v_pk_mul_f32 v[76:77], v[78:79], v[82:83] op_sel_hi:[1,0]
	v_exp_f32_e32 v84, v84
	v_exp_f32_e32 v85, v85
	v_exp_f32_e32 v76, v76
	v_exp_f32_e32 v77, v77
	v_cvt_pk_bf16_f32 v91, v80, v81
	v_pk_add_f32 v[84:85], v[84:85], 1.0 op_sel_hi:[1,0]
	v_add_u32_e32 v80, 32, v167
	v_rcp_f32_e32 v84, v84
	v_rcp_f32_e32 v85, v85
	v_mad_i64_i32 v[80:81], s[14:15], v80, s59, v[112:113]
	v_pk_add_f32 v[76:77], v[76:77], 1.0 op_sel_hi:[1,0]
	v_lshl_add_u64 v[80:81], v[80:81], 0, v[114:115]
	v_rcp_f32_e32 v76, v76
	v_rcp_f32_e32 v77, v77
	global_store_dwordx4 v[80:81], v[88:91], off sc1 nt
	v_mul_f32_e32 v80, v163, v163
	v_pk_mul_f32 v[74:75], v[78:79], v[74:75]
	v_pk_mul_f32 v[78:79], v[80:81], v[84:85] op_sel_hi:[0,1]
	v_pk_mul_f32 v[72:73], v[72:73], v[78:79]
	v_pk_mul_f32 v[78:79], v[68:69], v[82:83] op_sel_hi:[1,0]
	v_pk_mul_f32 v[76:77], v[80:81], v[76:77] op_sel_hi:[0,1]
	v_exp_f32_e32 v78, v78
	v_exp_f32_e32 v79, v79
	v_pk_mul_f32 v[74:75], v[74:75], v[76:77]
	v_pk_mul_f32 v[76:77], v[70:71], v[82:83] op_sel_hi:[1,0]
	v_cvt_pk_bf16_f32 v72, v72, v73
	v_cvt_pk_bf16_f32 v73, v74, v75
	v_pk_add_f32 v[74:75], v[78:79], 1.0 op_sel_hi:[1,0]
	v_exp_f32_e32 v76, v76
	v_exp_f32_e32 v77, v77
	v_rcp_f32_e32 v74, v74
	v_rcp_f32_e32 v75, v75
	v_pk_mul_f32 v[64:65], v[68:69], v[64:65]
	v_pk_add_f32 v[68:69], v[76:77], 1.0 op_sel_hi:[1,0]
	v_pk_mul_f32 v[66:67], v[70:71], v[66:67]
	v_rcp_f32_e32 v68, v68
	v_rcp_f32_e32 v69, v69
	v_pk_mul_f32 v[70:71], v[80:81], v[74:75] op_sel_hi:[0,1]
	v_pk_mul_f32 v[64:65], v[64:65], v[70:71]
	v_pk_mul_f32 v[56:57], v[60:61], v[56:57]
	v_cvt_pk_bf16_f32 v74, v64, v65
	v_pk_mul_f32 v[64:65], v[80:81], v[68:69] op_sel_hi:[0,1]
	v_pk_mul_f32 v[64:65], v[66:67], v[64:65]
	v_mul_f32_e32 v66, 0xbfb8aa3b, v142
	v_pk_mul_f32 v[68:69], v[60:61], v[66:67] op_sel_hi:[1,0]
	v_pk_mul_f32 v[60:61], v[62:63], v[66:67] op_sel_hi:[1,0]
	v_exp_f32_e32 v68, v68
	v_exp_f32_e32 v69, v69
	v_exp_f32_e32 v60, v60
	v_exp_f32_e32 v61, v61
	v_cvt_pk_bf16_f32 v75, v64, v65
	v_pk_add_f32 v[68:69], v[68:69], 1.0 op_sel_hi:[1,0]
	v_add_u32_e32 v64, 48, v167
	v_rcp_f32_e32 v68, v68
	v_rcp_f32_e32 v69, v69
	v_mad_i64_i32 v[64:65], s[14:15], v64, s59, v[112:113]
	v_pk_add_f32 v[60:61], v[60:61], 1.0 op_sel_hi:[1,0]
	v_lshl_add_u64 v[64:65], v[64:65], 0, v[114:115]
	v_rcp_f32_e32 v60, v60
	v_rcp_f32_e32 v61, v61
	global_store_dwordx4 v[64:65], v[72:75], off sc1 nt
	v_add_u32_e32 v65, 0x80, v167
	v_mul_f32_e32 v64, v142, v142
	v_pk_mul_f32 v[58:59], v[62:63], v[58:59]
	v_pk_mul_f32 v[62:63], v[64:65], v[68:69] op_sel_hi:[0,1]
	v_pk_mul_f32 v[56:57], v[56:57], v[62:63]
	v_pk_mul_f32 v[62:63], v[52:53], v[66:67] op_sel_hi:[1,0]
	v_pk_mul_f32 v[60:61], v[64:65], v[60:61] op_sel_hi:[0,1]
	v_exp_f32_e32 v62, v62
	v_exp_f32_e32 v63, v63
	v_pk_mul_f32 v[58:59], v[58:59], v[60:61]
	v_pk_mul_f32 v[60:61], v[54:55], v[66:67] op_sel_hi:[1,0]
	v_cvt_pk_bf16_f32 v56, v56, v57
	v_cvt_pk_bf16_f32 v57, v58, v59
	v_pk_add_f32 v[58:59], v[62:63], 1.0 op_sel_hi:[1,0]
	v_exp_f32_e32 v60, v60
	v_exp_f32_e32 v61, v61
	v_rcp_f32_e32 v58, v58
	v_rcp_f32_e32 v59, v59
	v_pk_mul_f32 v[48:49], v[52:53], v[48:49]
	v_pk_add_f32 v[52:53], v[60:61], 1.0 op_sel_hi:[1,0]
	v_pk_mul_f32 v[50:51], v[54:55], v[50:51]
	v_rcp_f32_e32 v52, v52
	v_rcp_f32_e32 v53, v53
	v_pk_mul_f32 v[54:55], v[64:65], v[58:59] op_sel_hi:[0,1]
	v_pk_mul_f32 v[48:49], v[48:49], v[54:55]
	v_pk_mul_f32 v[40:41], v[44:45], v[40:41]
	v_cvt_pk_bf16_f32 v58, v48, v49
	v_pk_mul_f32 v[48:49], v[64:65], v[52:53] op_sel_hi:[0,1]
	v_pk_mul_f32 v[48:49], v[50:51], v[48:49]
	v_mul_f32_e32 v50, 0xbfb8aa3b, v143
	v_pk_mul_f32 v[52:53], v[44:45], v[50:51] op_sel_hi:[1,0]
	v_pk_mul_f32 v[44:45], v[46:47], v[50:51] op_sel_hi:[1,0]
	v_exp_f32_e32 v52, v52
	v_exp_f32_e32 v53, v53
	v_exp_f32_e32 v44, v44
	v_exp_f32_e32 v45, v45
	v_cvt_pk_bf16_f32 v59, v48, v49
	v_pk_add_f32 v[52:53], v[52:53], 1.0 op_sel_hi:[1,0]
	v_mad_i64_i32 v[48:49], s[14:15], v65, s59, v[112:113]
	v_rcp_f32_e32 v52, v52
	v_rcp_f32_e32 v53, v53
	v_pk_add_f32 v[44:45], v[44:45], 1.0 op_sel_hi:[1,0]
	v_lshl_add_u64 v[48:49], v[48:49], 0, v[114:115]
	v_rcp_f32_e32 v44, v44
	v_rcp_f32_e32 v45, v45
	global_store_dwordx4 v[48:49], v[56:59], off sc1 nt
	v_mul_f32_e32 v48, v143, v143
	v_pk_mul_f32 v[42:43], v[46:47], v[42:43]
; __device__ __forceinline__ unsigned cvt_pk_bf16(float lo, float hi) { unsigned r; asm volatile("v_cvt_pk_bf16_f32 %0, %1, %2" : "=v"(r) : "v"(lo), "v"(hi)); return r; }
;     __device__ __forceinline__ void operator()(const f32x4 (&acc)[2][2][4][2], const Unit& u, int ui, int wr, int wc, int fr, int fq) const {
;     ...
;             for (int m = 0; m < 4; ++m) { const float r = rs[ai][m]; const int row = row0 + ai * HALF + m * 16;
;                 const float c1 = r * -1.44269504089f, r2 = r * r; u32x4 w;
; #pragma unroll
;                 for (int n = 0; n < 2; ++n)
; #pragma unroll
;                     for (int p = 0; p < 2; ++p) { const f32x2 g = (f32x2){acc[ai][0][m][n][2 * p], acc[ai][0][m][n][2 * p + 1]}, uu = (f32x2){acc[ai][1][m][n][2 * p], acc[ai][1][m][n][2 * p + 1]};
;                         const f32x2 t = g * c1; f32x2 d; d.x = __builtin_amdgcn_exp2f(t.x); d.y = __builtin_amdgcn_exp2f(t.y); d = d + 1.0f;
;                         f32x2 q; q.x = __builtin_amdgcn_rcpf(d.x); q.y = __builtin_amdgcn_rcpf(d.y);
;                         const f32x2 hh = (g * uu) * (q * r2); w[2 * n + p] = cvt_pk_bf16(hh.x, hh.y); }
;                 __builtin_nontemporal_store(w, (u32x4*)(H + (size_t)row * ldh + col0)); }
	v_pk_mul_f32 v[46:47], v[48:49], v[52:53] op_sel_hi:[0,1]
	v_pk_mul_f32 v[40:41], v[40:41], v[46:47]
	v_pk_mul_f32 v[46:47], v[36:37], v[50:51] op_sel_hi:[1,0]
	v_pk_mul_f32 v[44:45], v[48:49], v[44:45] op_sel_hi:[0,1]
	v_exp_f32_e32 v46, v46
	v_exp_f32_e32 v47, v47
	v_pk_mul_f32 v[42:43], v[42:43], v[44:45]
	v_pk_mul_f32 v[44:45], v[38:39], v[50:51] op_sel_hi:[1,0]
	v_cvt_pk_bf16_f32 v40, v40, v41
	v_cvt_pk_bf16_f32 v41, v42, v43
	v_pk_add_f32 v[42:43], v[46:47], 1.0 op_sel_hi:[1,0]
	v_exp_f32_e32 v44, v44
	v_exp_f32_e32 v45, v45
	v_rcp_f32_e32 v42, v42
	v_rcp_f32_e32 v43, v43
	v_pk_mul_f32 v[32:33], v[36:37], v[32:33]
	v_pk_add_f32 v[36:37], v[44:45], 1.0 op_sel_hi:[1,0]
	v_pk_mul_f32 v[34:35], v[38:39], v[34:35]
	v_rcp_f32_e32 v36, v36
	v_rcp_f32_e32 v37, v37
	v_pk_mul_f32 v[38:39], v[48:49], v[42:43] op_sel_hi:[0,1]
	v_pk_mul_f32 v[32:33], v[32:33], v[38:39]
	v_pk_mul_f32 v[24:25], v[28:29], v[24:25]
	v_cvt_pk_bf16_f32 v42, v32, v33
	v_pk_mul_f32 v[32:33], v[48:49], v[36:37] op_sel_hi:[0,1]
	v_pk_mul_f32 v[32:33], v[34:35], v[32:33]
	v_mul_f32_e32 v34, 0xbfb8aa3b, v140
	v_pk_mul_f32 v[36:37], v[28:29], v[34:35] op_sel_hi:[1,0]
	v_pk_mul_f32 v[28:29], v[30:31], v[34:35] op_sel_hi:[1,0]
	v_exp_f32_e32 v36, v36
	v_exp_f32_e32 v37, v37
	v_exp_f32_e32 v28, v28
	v_exp_f32_e32 v29, v29
	v_cvt_pk_bf16_f32 v43, v32, v33
	v_pk_add_f32 v[36:37], v[36:37], 1.0 op_sel_hi:[1,0]
	v_add_u32_e32 v32, 0x90, v167
	v_rcp_f32_e32 v36, v36
	v_rcp_f32_e32 v37, v37
	v_mad_i64_i32 v[32:33], s[14:15], v32, s59, v[112:113]
	v_pk_add_f32 v[28:29], v[28:29], 1.0 op_sel_hi:[1,0]
	v_lshl_add_u64 v[32:33], v[32:33], 0, v[114:115]
	v_rcp_f32_e32 v28, v28
	v_rcp_f32_e32 v29, v29
	global_store_dwordx4 v[32:33], v[40:43], off sc1 nt
	v_mul_f32_e32 v32, v140, v140
	v_pk_mul_f32 v[26:27], v[30:31], v[26:27]
	v_pk_mul_f32 v[30:31], v[32:33], v[36:37] op_sel_hi:[0,1]
	v_pk_mul_f32 v[24:25], v[24:25], v[30:31]
	v_pk_mul_f32 v[30:31], v[20:21], v[34:35] op_sel_hi:[1,0]
	v_pk_mul_f32 v[28:29], v[32:33], v[28:29] op_sel_hi:[0,1]
	v_exp_f32_e32 v30, v30
	v_exp_f32_e32 v31, v31
	v_pk_mul_f32 v[26:27], v[26:27], v[28:29]
	v_pk_mul_f32 v[28:29], v[22:23], v[34:35] op_sel_hi:[1,0]
	v_cvt_pk_bf16_f32 v24, v24, v25
	v_cvt_pk_bf16_f32 v25, v26, v27
	v_pk_add_f32 v[26:27], v[30:31], 1.0 op_sel_hi:[1,0]
	v_exp_f32_e32 v28, v28
	v_exp_f32_e32 v29, v29
	v_rcp_f32_e32 v26, v26
	v_rcp_f32_e32 v27, v27
	v_pk_mul_f32 v[16:17], v[20:21], v[16:17]
	v_pk_add_f32 v[20:21], v[28:29], 1.0 op_sel_hi:[1,0]
	v_pk_mul_f32 v[18:19], v[22:23], v[18:19]
	v_rcp_f32_e32 v20, v20
	v_rcp_f32_e32 v21, v21
	v_pk_mul_f32 v[22:23], v[32:33], v[26:27] op_sel_hi:[0,1]
	v_pk_mul_f32 v[16:17], v[16:17], v[22:23]
	v_pk_mul_f32 v[8:9], v[12:13], v[8:9]
	v_cvt_pk_bf16_f32 v26, v16, v17
	v_pk_mul_f32 v[16:17], v[32:33], v[20:21] op_sel_hi:[0,1]
	v_pk_mul_f32 v[16:17], v[18:19], v[16:17]
	v_mul_f32_e32 v18, 0xbfb8aa3b, v141
	v_pk_mul_f32 v[20:21], v[12:13], v[18:19] op_sel_hi:[1,0]
	v_pk_mul_f32 v[12:13], v[14:15], v[18:19] op_sel_hi:[1,0]
	v_exp_f32_e32 v20, v20
	v_exp_f32_e32 v21, v21
	v_exp_f32_e32 v12, v12
	v_exp_f32_e32 v13, v13
	v_cvt_pk_bf16_f32 v27, v16, v17
	v_pk_add_f32 v[20:21], v[20:21], 1.0 op_sel_hi:[1,0]
	v_add_u32_e32 v16, 0xa0, v167
	v_rcp_f32_e32 v20, v20
	v_rcp_f32_e32 v21, v21
	v_mad_i64_i32 v[16:17], s[14:15], v16, s59, v[112:113]
	v_pk_add_f32 v[12:13], v[12:13], 1.0 op_sel_hi:[1,0]
	v_lshl_add_u64 v[16:17], v[16:17], 0, v[114:115]
	v_rcp_f32_e32 v12, v12
	v_rcp_f32_e32 v13, v13
	global_store_dwordx4 v[16:17], v[24:27], off sc1 nt
	v_mul_f32_e32 v16, v141, v141
	v_pk_mul_f32 v[10:11], v[14:15], v[10:11]
	v_pk_mul_f32 v[14:15], v[16:17], v[20:21] op_sel_hi:[0,1]
	v_pk_mul_f32 v[8:9], v[8:9], v[14:15]
	v_pk_mul_f32 v[14:15], v[4:5], v[18:19] op_sel_hi:[1,0]
	v_pk_mul_f32 v[12:13], v[16:17], v[12:13] op_sel_hi:[0,1]
	v_exp_f32_e32 v14, v14
	v_exp_f32_e32 v15, v15
	v_pk_mul_f32 v[10:11], v[10:11], v[12:13]
	v_pk_mul_f32 v[12:13], v[6:7], v[18:19] op_sel_hi:[1,0]
	v_cvt_pk_bf16_f32 v8, v8, v9
	v_cvt_pk_bf16_f32 v9, v10, v11
	v_pk_add_f32 v[10:11], v[14:15], 1.0 op_sel_hi:[1,0]
	v_exp_f32_e32 v12, v12
	v_exp_f32_e32 v13, v13
	v_rcp_f32_e32 v10, v10
	v_rcp_f32_e32 v11, v11
	v_pk_mul_f32 v[0:1], v[4:5], v[0:1]
	v_pk_add_f32 v[4:5], v[12:13], 1.0 op_sel_hi:[1,0]
	v_pk_mul_f32 v[2:3], v[6:7], v[2:3]
	v_rcp_f32_e32 v4, v4
	v_rcp_f32_e32 v5, v5
	v_pk_mul_f32 v[6:7], v[16:17], v[10:11] op_sel_hi:[0,1]
	v_pk_mul_f32 v[0:1], v[0:1], v[6:7]
	s_andn2_b64 vcc, exec, s[8:9]
	v_cvt_pk_bf16_f32 v10, v0, v1
	v_pk_mul_f32 v[0:1], v[16:17], v[4:5] op_sel_hi:[0,1]
	v_pk_mul_f32 v[0:1], v[2:3], v[0:1]
	s_mov_b64 s[8:9], -1
	v_cvt_pk_bf16_f32 v11, v0, v1
	v_add_u32_e32 v0, 0xb0, v167
	v_mad_i64_i32 v[0:1], s[14:15], v0, s59, v[112:113]
	v_lshl_add_u64 v[0:1], v[0:1], 0, v[114:115]
	global_store_dwordx4 v[0:1], v[8:11], off sc1 nt
	s_cbranch_vccnz .LBB0_442
	s_andn2_b64 vcc, exec, s[0:1]
	s_cbranch_vccnz .LBB0_441
	s_barrier
	s_branch .LBB0_441
